# rwb: waves 4-7 enter the n-tile loop a fraction of a step after waves 0-3 so the two waves of a SIMD alternate between their LDS/MFMA and VALU phases
# baseline (speedup 1.0000x reference)
; __device__ __forceinline__ float tanhf_(float x) { const float e = __expf(2.0f * fminf(fmaxf(x, -15.f), 15.f)); return (e - 1.0f) * __builtin_amdgcn_rcpf(e + 1.0f); }
; __device__ __forceinline__ void phase_rwb(const int wvs, const Params& p, LAS unsigned char* lds, int layer) {
;     ...
;   for (int d = 0; d < 2; ++d) {
;     h8 bw[2], ba[2];
; #pragma unroll
;     for (int ks = 0; ks < 2; ++ks) { const h8 x = *(const h8*)(P + tok * PP + PC_RL2 + d * 64 + ks * 32 + fq * 8);
; #pragma unroll
;       for (int j = 0; j < 8; ++j) bw[ks][j] = (hf)tanhf_((float)x[j]);
;       ba[ks] = *(const h8*)(P + tok * PP + PC_RL2 + 128 + d * 64 + ks * 32 + fq * 8); }
;     { h8 sw[6], sa[6];
; #pragma unroll
;       for (int j = 0; j < 6; ++j) { const int idx = tid + 512 * j; const size_t wo = ((size_t)d * 384 + (idx >> 3)) * 64 + (idx & 7) * 8; sw[j] = *(const h8*)(wupT + wo); sa[j] = *(const h8*)(aupT + wo); }
;       __syncthreads();
.LBB0_1145:
	s_lshl_b32 s30, s6, 7
	v_lshl_add_u64 v[14:15], v[66:67], 0, s[30:31]
	global_load_dwordx4 v[2:5], v[14:15], off offset:3584
	s_mul_i32 s30, s6, 0x180
	v_lshl_add_u64 v[26:27], s[30:31], 0, v[70:71]
	v_lshlrev_b64 v[30:31], 7, v[26:27]
	v_or_b32_e32 v30, v30, v0
	v_lshl_add_u64 v[34:35], s[30:31], 0, v[72:73]
	v_lshl_add_u64 v[26:27], s[8:9], 0, v[30:31]
	v_lshlrev_b64 v[38:39], 7, v[34:35]
	v_lshl_add_u64 v[30:31], s[10:11], 0, v[30:31]
	v_or_b32_e32 v38, v38, v0
	v_lshl_add_u64 v[42:43], s[30:31], 0, v[74:75]
	v_lshl_add_u64 v[34:35], s[8:9], 0, v[38:39]
	v_lshlrev_b64 v[46:47], 7, v[42:43]
	v_lshl_add_u64 v[38:39], s[10:11], 0, v[38:39]
	v_or_b32_e32 v46, v46, v0
	v_lshl_add_u64 v[50:51], s[30:31], 0, v[76:77]
	v_lshl_add_u64 v[42:43], s[8:9], 0, v[46:47]
	v_lshlrev_b64 v[54:55], 7, v[50:51]
	v_lshl_add_u64 v[46:47], s[10:11], 0, v[46:47]
	v_or_b32_e32 v54, v54, v0
	v_lshl_add_u64 v[58:59], s[30:31], 0, v[78:79]
	v_lshl_add_u64 v[50:51], s[8:9], 0, v[54:55]
	v_lshlrev_b64 v[62:63], 7, v[58:59]
	v_lshl_add_u64 v[54:55], s[10:11], 0, v[54:55]
	v_or_b32_e32 v62, v62, v0
	v_lshl_add_u64 v[58:59], s[8:9], 0, v[62:63]
	v_lshl_add_u64 v[62:63], s[10:11], 0, v[62:63]
	s_or_b32 s2, s6, s16
	s_xor_b64 s[12:13], s[4:5], -1
	s_mov_b64 s[14:15], 0
	s_waitcnt vmcnt(0)
	v_cvt_f32_f16_e32 v6, v2
	v_cvt_f32_f16_sdwa v2, v2 dst_sel:DWORD dst_unused:UNUSED_PAD src0_sel:WORD_1
	v_med3_f32 v6, v6, s70, v223
	v_add_f32_e32 v6, v6, v6
	v_mul_f32_e32 v6, 0x3fb8aa3b, v6
	v_exp_f32_e32 v6, v6
	v_med3_f32 v2, v2, s70, v223
	v_add_f32_e32 v2, v2, v2
	v_mul_f32_e32 v2, 0x3fb8aa3b, v2
	v_add_f32_e32 v7, 1.0, v6
	v_rcp_f32_e32 v8, v7
	v_exp_f32_e32 v7, v2
	s_nop 0
	v_add_f32_e32 v2, 1.0, v7
	v_rcp_f32_e32 v9, v2
	v_pk_add_f32 v[6:7], v[6:7], -1.0 op_sel_hi:[1,0]
	s_nop 0
	v_pk_mul_f32 v[6:7], v[6:7], v[8:9]
	s_nop 0
	v_cvt_pk_f16_f32 v2, v6, v7
	v_cvt_f32_f16_e32 v6, v3
	v_cvt_f32_f16_sdwa v3, v3 dst_sel:DWORD dst_unused:UNUSED_PAD src0_sel:WORD_1
	v_med3_f32 v6, v6, s70, v223
	v_add_f32_e32 v6, v6, v6
	v_mul_f32_e32 v6, 0x3fb8aa3b, v6
	v_exp_f32_e32 v6, v6
	v_med3_f32 v3, v3, s70, v223
	v_add_f32_e32 v3, v3, v3
	v_mul_f32_e32 v3, 0x3fb8aa3b, v3
	v_add_f32_e32 v7, 1.0, v6
	v_rcp_f32_e32 v8, v7
	v_exp_f32_e32 v7, v3
	s_nop 0
	v_add_f32_e32 v3, 1.0, v7
	v_rcp_f32_e32 v9, v3
	v_pk_add_f32 v[6:7], v[6:7], -1.0 op_sel_hi:[1,0]
	s_nop 0
	v_pk_mul_f32 v[6:7], v[6:7], v[8:9]
	s_nop 0
	v_cvt_pk_f16_f32 v3, v6, v7
	v_cvt_f32_f16_e32 v6, v4
	v_cvt_f32_f16_sdwa v4, v4 dst_sel:DWORD dst_unused:UNUSED_PAD src0_sel:WORD_1
	v_med3_f32 v6, v6, s70, v223
	v_add_f32_e32 v6, v6, v6
	v_mul_f32_e32 v6, 0x3fb8aa3b, v6
	v_exp_f32_e32 v6, v6
	v_med3_f32 v4, v4, s70, v223
	v_add_f32_e32 v4, v4, v4
	v_mul_f32_e32 v4, 0x3fb8aa3b, v4
	v_add_f32_e32 v7, 1.0, v6
	v_rcp_f32_e32 v8, v7
	v_exp_f32_e32 v7, v4
	s_nop 0
	v_add_f32_e32 v4, 1.0, v7
	v_rcp_f32_e32 v9, v4
	v_pk_add_f32 v[6:7], v[6:7], -1.0 op_sel_hi:[1,0]
	s_nop 0
	v_pk_mul_f32 v[6:7], v[6:7], v[8:9]
	s_nop 0
	v_cvt_pk_f16_f32 v4, v6, v7
	v_cvt_f32_f16_e32 v6, v5
	v_cvt_f32_f16_sdwa v5, v5 dst_sel:DWORD dst_unused:UNUSED_PAD src0_sel:WORD_1
	v_med3_f32 v6, v6, s70, v223
	v_add_f32_e32 v6, v6, v6
	v_mul_f32_e32 v6, 0x3fb8aa3b, v6
	v_exp_f32_e32 v6, v6
	v_med3_f32 v5, v5, s70, v223
	v_add_f32_e32 v5, v5, v5
	v_mul_f32_e32 v5, 0x3fb8aa3b, v5
	v_add_f32_e32 v7, 1.0, v6
	v_rcp_f32_e32 v8, v7
	v_exp_f32_e32 v7, v5
	s_nop 0
	v_add_f32_e32 v5, 1.0, v7
	v_rcp_f32_e32 v9, v5
	v_pk_add_f32 v[6:7], v[6:7], -1.0 op_sel_hi:[1,0]
	s_nop 0
	v_pk_mul_f32 v[6:7], v[6:7], v[8:9]
	s_nop 0
	v_cvt_pk_f16_f32 v5, v6, v7
	global_load_dwordx4 v[6:9], v[14:15], off offset:3840
	global_load_dwordx4 v[10:13], v[14:15], off offset:3648
	s_waitcnt vmcnt(0)
	v_cvt_f32_f16_e32 v16, v10
	v_cvt_f32_f16_sdwa v10, v10 dst_sel:DWORD dst_unused:UNUSED_PAD src0_sel:WORD_1
	global_load_dwordx4 v[30:33], v[30:31], off
	v_med3_f32 v16, v16, s70, v223
	v_add_f32_e32 v16, v16, v16
	v_mul_f32_e32 v16, 0x3fb8aa3b, v16
	v_exp_f32_e32 v16, v16
	v_med3_f32 v10, v10, s70, v223
	v_add_f32_e32 v10, v10, v10
	v_mul_f32_e32 v10, 0x3fb8aa3b, v10
	v_add_f32_e32 v17, 1.0, v16
	v_rcp_f32_e32 v18, v17
	v_exp_f32_e32 v17, v10
	global_load_dwordx4 v[34:37], v[34:35], off
	v_add_f32_e32 v10, 1.0, v17
	v_rcp_f32_e32 v19, v10
	v_pk_add_f32 v[16:17], v[16:17], -1.0 op_sel_hi:[1,0]
	global_load_dwordx4 v[38:41], v[38:39], off
	v_pk_mul_f32 v[16:17], v[16:17], v[18:19]
	s_nop 0
	v_cvt_pk_f16_f32 v10, v16, v17
	v_cvt_f32_f16_e32 v16, v11
	v_cvt_f32_f16_sdwa v11, v11 dst_sel:DWORD dst_unused:UNUSED_PAD src0_sel:WORD_1
	global_load_dwordx4 v[42:45], v[42:43], off
	v_med3_f32 v16, v16, s70, v223
	v_add_f32_e32 v16, v16, v16
	v_mul_f32_e32 v16, 0x3fb8aa3b, v16
	v_exp_f32_e32 v16, v16
	v_med3_f32 v11, v11, s70, v223
	v_add_f32_e32 v11, v11, v11
	v_mul_f32_e32 v11, 0x3fb8aa3b, v11
	v_add_f32_e32 v17, 1.0, v16
	v_rcp_f32_e32 v18, v17
	v_exp_f32_e32 v17, v11
	global_load_dwordx4 v[46:49], v[46:47], off
	v_add_f32_e32 v11, 1.0, v17
	v_rcp_f32_e32 v19, v11
	v_pk_add_f32 v[16:17], v[16:17], -1.0 op_sel_hi:[1,0]
	global_load_dwordx4 v[50:53], v[50:51], off
	v_pk_mul_f32 v[16:17], v[16:17], v[18:19]
	s_nop 0
	v_cvt_pk_f16_f32 v11, v16, v17
	v_cvt_f32_f16_e32 v16, v12
	v_cvt_f32_f16_sdwa v12, v12 dst_sel:DWORD dst_unused:UNUSED_PAD src0_sel:WORD_1
	global_load_dwordx4 v[54:57], v[54:55], off
	v_med3_f32 v16, v16, s70, v223
	v_add_f32_e32 v16, v16, v16
	v_mul_f32_e32 v16, 0x3fb8aa3b, v16
	v_exp_f32_e32 v16, v16
	v_med3_f32 v12, v12, s70, v223
	v_add_f32_e32 v12, v12, v12
	v_mul_f32_e32 v12, 0x3fb8aa3b, v12
	v_add_f32_e32 v17, 1.0, v16
	v_rcp_f32_e32 v18, v17
	v_exp_f32_e32 v17, v12
	global_load_dwordx4 v[58:61], v[58:59], off
	v_add_f32_e32 v12, 1.0, v17
	v_rcp_f32_e32 v19, v12
	v_pk_add_f32 v[16:17], v[16:17], -1.0 op_sel_hi:[1,0]
	global_load_dwordx4 v[62:65], v[62:63], off
	v_pk_mul_f32 v[16:17], v[16:17], v[18:19]
	s_nop 0
	v_cvt_pk_f16_f32 v12, v16, v17
	v_cvt_f32_f16_e32 v16, v13
	v_cvt_f32_f16_sdwa v13, v13 dst_sel:DWORD dst_unused:UNUSED_PAD src0_sel:WORD_1
	global_load_dwordx4 v[26:29], v[26:27], off
	v_med3_f32 v16, v16, s70, v223
	v_add_f32_e32 v16, v16, v16
	v_mul_f32_e32 v16, 0x3fb8aa3b, v16
	v_exp_f32_e32 v16, v16
	v_med3_f32 v13, v13, s70, v223
	v_add_f32_e32 v13, v13, v13
	v_mul_f32_e32 v13, 0x3fb8aa3b, v13
	v_add_f32_e32 v17, 1.0, v16
	v_rcp_f32_e32 v18, v17
	v_exp_f32_e32 v17, v13
	s_nop 0
	v_add_f32_e32 v13, 1.0, v17
	v_rcp_f32_e32 v19, v13
	v_pk_add_f32 v[16:17], v[16:17], -1.0 op_sel_hi:[1,0]
	s_nop 0
	v_pk_mul_f32 v[16:17], v[16:17], v[18:19]
	v_lshl_add_u64 v[18:19], s[30:31], 0, v[68:69]
	v_lshlrev_b64 v[22:23], 7, v[18:19]
	v_or_b32_e32 v22, v22, v0
	v_lshl_add_u64 v[18:19], s[8:9], 0, v[22:23]
	v_cvt_pk_f16_f32 v13, v16, v17
	global_load_dwordx4 v[14:17], v[14:15], off offset:3904
	v_lshl_add_u64 v[22:23], s[10:11], 0, v[22:23]
	global_load_dwordx4 v[18:21], v[18:19], off
	s_mul_i32 s30, s2, 0x180
	global_load_dwordx4 v[22:25], v[22:23], off
	s_barrier
; #define LAS __attribute__((address_space(3)))
; __device__ __forceinline__ float sigmoidf_(float x) { return __builtin_amdgcn_rcpf(1.0f + __expf(-x)); }
; __device__ __forceinline__ float softplusf_(float x) { return x > 20.f ? x : __logf(1.0f + __expf(x)); }
; __device__ __forceinline__ f32x4 mfma16(h8 a, h8 b, f32x4 c) { return __builtin_amdgcn_mfma_f32_16x16x32_f16(a, b, c, 0, 0, 0); }
; __device__ __forceinline__ void phase_rwb(const int wvs, const Params& p, LAS unsigned char* lds, int layer) {
;     ...
;       __syncthreads();
; #pragma unroll
;       for (int j = 0; j < 6; ++j) { const int idx = tid + 512 * j; *(LAS h8*)(lds + (idx >> 3) * 144 + (idx & 7) * 16) = sw[j]; *(LAS h8*)(lds + 55296 + (idx >> 3) * 144 + (idx & 7) * 16) = sa[j]; }
;       __syncthreads(); }
;     const float* w0 = p.in[I_W0] + (layer * 2 + d) * 384; const float* a0 = p.in[I_A0] + (layer * 2 + d) * 384;
; #pragma unroll 2
;     for (int nt = 0; nt < 24; ++nt) { f32x4 aw = {0.f, 0.f, 0.f, 0.f}, aa = {0.f, 0.f, 0.f, 0.f};
;       const int n4 = nt * 16 + fq * 4; const f32x4 w04 = *(const f32x4*)(w0 + n4), a04 = *(const f32x4*)(a0 + n4);
; #pragma unroll
;       for (int ks = 0; ks < 2; ++ks) { aw = mfma16(*(const LAS h8*)(lds + (nt * 16 + fr) * 144 + ks * 64 + fq * 16), bw[ks], aw); aa = mfma16(*(const LAS h8*)(lds + 55296 + (nt * 16 + fr) * 144 + ks * 64 + fq * 16), ba[ks], aa); }
;       h4 oe, oa;
; #pragma unroll
;       for (int r = 0; r < 4; ++r) { const float wl = -softplusf_(-(w04[r] + aw[r])) - 0.5f; oe[r] = (hf)__expf(wl); oa[r] = (hf)sigmoidf_(a04[r] + aa[r]); }
	s_waitcnt vmcnt(1)
	ds_write_b128 v87, v[18:21]
	s_waitcnt vmcnt(0)
	ds_write_b128 v87, v[22:25] offset:55296
	ds_write_b128 v88, v[26:29]
	ds_write_b128 v88, v[30:33] offset:55296
	ds_write_b128 v89, v[34:37]
	ds_write_b128 v89, v[38:41] offset:55296
	ds_write_b128 v90, v[42:45]
	ds_write_b128 v90, v[46:49] offset:55296
	ds_write_b128 v91, v[50:53]
	ds_write_b128 v91, v[54:57] offset:55296
	ds_write_b128 v92, v[58:61]
	ds_write_b128 v92, v[62:65] offset:55296
	v_mov_b32_e32 v18, 0x300
	v_mad_u64_u32 v[26:27], s[4:5], s6, v18, v[80:81]
	s_lshl_b64 s[4:5], s[30:31], 2
	s_nop 0
	v_lshl_add_u64 v[28:29], v[82:83], 0, s[4:5]
	v_lshl_add_u64 v[30:31], v[84:85], 0, s[4:5]
	v_mov_b32_e32 v32, v86
	s_waitcnt lgkmcnt(0)
	s_barrier
	v_readfirstlane_b32 s4, v193
	s_nop 0
	s_cmp_lt_u32 s4, 0x100
	s_cbranch_scc1 .Lrwb_go
	s_sleep 8
.Lrwb_go:
.LBB0_1146:
	v_lshl_add_u64 v[46:47], v[30:31], 0, s[14:15]
	global_load_dwordx4 v[18:21], v[46:47], off
	v_lshl_add_u64 v[48:49], v[28:29], 0, s[14:15]
	global_load_dwordx4 v[22:25], v[48:49], off
	ds_read_b128 v[34:37], v32
	ds_read_b128 v[42:45], v32 offset:64
	ds_read_b128 v[38:41], v32 offset:55296
	s_add_u32 s14, s14, 0x80
	s_addc_u32 s15, s15, 0
	s_waitcnt lgkmcnt(2)
	v_mfma_f32_16x16x32_f16 v[34:37], v[34:37], v[2:5], 0
	s_cmpk_eq_i32 s14, 0x600
	s_waitcnt lgkmcnt(1)
	v_mfma_f32_16x16x32_f16 v[34:37], v[42:45], v[10:13], v[34:37]
	ds_read_b128 v[42:45], v32 offset:55360
	s_waitcnt lgkmcnt(1)
	v_mfma_f32_16x16x32_f16 v[38:41], v[38:41], v[6:9], 0
	s_waitcnt lgkmcnt(0)
	v_mfma_f32_16x16x32_f16 v[38:41], v[42:45], v[14:17], v[38:41]
	s_waitcnt vmcnt(1)
	s_nop 1
	v_add_f32_e32 v18, v18, v34
	v_mul_f32_e32 v33, 0xbfb8aa3b, v18
	v_exp_f32_e32 v33, v33
	v_cmp_gt_f32_e32 vcc, s71, v18
	v_add_f32_e32 v19, v19, v35
	v_add_f32_e32 v21, v21, v37
	v_add_f32_e32 v33, 1.0, v33
	v_cmp_gt_f32_e64 s[4:5], s34, v33
	s_waitcnt vmcnt(0)
	v_add_f32_e32 v22, v22, v38
	v_mul_f32_e32 v22, 0xbfb8aa3b, v22
	v_cndmask_b32_e64 v34, 0, 32, s[4:5]
	v_ldexp_f32 v33, v33, v34
	v_log_f32_e32 v33, v33
	v_exp_f32_e32 v22, v22
	v_mul_f32_e32 v34, 0x3f317217, v33
	v_fma_f32 v34, v33, s66, -v34
	v_fmac_f32_e32 v34, 0x3377d1cf, v33
	v_fmac_f32_e32 v34, 0x3f317217, v33
	v_cmp_lt_f32_e64 s[6:7], |v33|, s65
	v_add_f32_e32 v22, 1.0, v22
	v_rcp_f32_e32 v22, v22
	v_cndmask_b32_e64 v33, v33, v34, s[6:7]
	v_cndmask_b32_e64 v34, 0, v220, s[4:5]
	v_sub_f32_e32 v33, v33, v34
	v_cndmask_b32_e64 v18, v33, -v18, vcc
	v_mul_f32_e32 v33, 0xbfb8aa3b, v19
	v_exp_f32_e32 v33, v33
	v_cmp_gt_f32_e32 vcc, s71, v19
	v_sub_f32_e32 v18, -0.5, v18
	v_mul_f32_e32 v18, 0x3fb8aa3b, v18
	v_add_f32_e32 v33, 1.0, v33
	v_cmp_gt_f32_e64 s[4:5], s34, v33
	v_exp_f32_e32 v18, v18
	s_nop 0
	v_cndmask_b32_e64 v34, 0, 32, s[4:5]
	v_ldexp_f32 v33, v33, v34
	v_log_f32_e32 v33, v33
	s_nop 0
	v_mul_f32_e32 v34, 0x3f317217, v33
	v_fma_f32 v34, v33, s66, -v34
	v_fmac_f32_e32 v34, 0x3377d1cf, v33
	v_fmac_f32_e32 v34, 0x3f317217, v33
	v_cmp_lt_f32_e64 s[6:7], |v33|, s65
	s_nop 1
	v_cndmask_b32_e64 v33, v33, v34, s[6:7]
	v_cndmask_b32_e64 v34, 0, v220, s[4:5]
	v_sub_f32_e32 v33, v33, v34
	v_cndmask_b32_e64 v19, v33, -v19, vcc
	v_sub_f32_e32 v19, -0.5, v19
	v_mul_f32_e32 v19, 0x3fb8aa3b, v19
	v_exp_f32_e32 v33, v19
	v_add_f32_e32 v19, v23, v39
	v_mul_f32_e32 v19, 0xbfb8aa3b, v19
	v_exp_f32_e32 v19, v19
	v_cvt_pk_f16_f32 v18, v18, v33
	v_add_f32_e32 v19, 1.0, v19
	v_rcp_f32_e32 v23, v19
	v_add_f32_e32 v19, v20, v36
	v_mul_f32_e32 v20, 0xbfb8aa3b, v19
	v_exp_f32_e32 v20, v20
	v_cmp_gt_f32_e32 vcc, s71, v19
	v_add_f32_e32 v20, 1.0, v20
	v_cmp_gt_f32_e64 s[4:5], s34, v20
	s_nop 1
	v_cndmask_b32_e64 v34, 0, 32, s[4:5]
	v_ldexp_f32 v20, v20, v34
	v_log_f32_e32 v20, v20
	s_nop 0
	v_mul_f32_e32 v34, 0x3f317217, v20
	v_fma_f32 v34, v20, s66, -v34
	v_fmac_f32_e32 v34, 0x3377d1cf, v20
	v_fmac_f32_e32 v34, 0x3f317217, v20
	v_cmp_lt_f32_e64 s[6:7], |v20|, s65
	s_nop 1
	v_cndmask_b32_e64 v20, v20, v34, s[6:7]
	v_cndmask_b32_e64 v34, 0, v220, s[4:5]
	v_sub_f32_e32 v20, v20, v34
	v_cndmask_b32_e64 v19, v20, -v19, vcc
	v_add_f32_e32 v20, v24, v40
	v_mul_f32_e32 v24, 0xbfb8aa3b, v21
	v_exp_f32_e32 v24, v24
	v_cmp_gt_f32_e32 vcc, s71, v21
	v_sub_f32_e32 v19, -0.5, v19
	v_mul_f32_e32 v19, 0x3fb8aa3b, v19
	v_add_f32_e32 v24, 1.0, v24
	v_cmp_gt_f32_e64 s[4:5], s34, v24
	v_exp_f32_e32 v19, v19
	v_mul_f32_e32 v20, 0xbfb8aa3b, v20
	v_cndmask_b32_e64 v34, 0, 32, s[4:5]
	v_ldexp_f32 v24, v24, v34
	v_log_f32_e32 v24, v24
	v_exp_f32_e32 v20, v20
	v_mul_f32_e32 v34, 0x3f317217, v24
	v_fma_f32 v34, v24, s66, -v34
	v_fmac_f32_e32 v34, 0x3377d1cf, v24
	v_fmac_f32_e32 v34, 0x3f317217, v24
	v_cmp_lt_f32_e64 s[6:7], |v24|, s65
	v_add_f32_e32 v20, 1.0, v20
	v_rcp_f32_e32 v20, v20
	v_cndmask_b32_e64 v24, v24, v34, s[6:7]
	v_cndmask_b32_e64 v34, 0, v220, s[4:5]
	v_sub_f32_e32 v24, v24, v34
	v_cndmask_b32_e64 v21, v24, -v21, vcc
	v_sub_f32_e32 v21, -0.5, v21
	v_mul_f32_e32 v21, 0x3fb8aa3b, v21
	v_exp_f32_e32 v21, v21
	s_nop 0
	v_cvt_pk_f16_f32 v19, v19, v21
	v_add_f32_e32 v21, v25, v41
	v_mul_f32_e32 v21, 0xbfb8aa3b, v21
	v_exp_f32_e32 v21, v21
	s_nop 0
	v_add_f32_e32 v21, 1.0, v21
	v_rcp_f32_e32 v21, v21
	s_nop 0
	v_cvt_pk_f16_f32 v21, v20, v21
	v_cvt_pk_f16_f32 v20, v22, v23
	global_store_dwordx2 v[26:27], v[18:19], off offset:-1536
	global_store_dwordx2 v[26:27], v[20:21], off
	global_load_dwordx4 v[22:25], v[46:47], off offset:64
	s_nop 0
	global_load_dwordx4 v[18:21], v[48:49], off offset:64
	ds_read_b128 v[34:37], v32 offset:2304
	ds_read_b128 v[42:45], v32 offset:2368
	s_waitcnt lgkmcnt(1)
; #define LAS __attribute__((address_space(3)))
; __device__ __forceinline__ float sigmoidf_(float x) { return __builtin_amdgcn_rcpf(1.0f + __expf(-x)); }
; __device__ __forceinline__ float softplusf_(float x) { return x > 20.f ? x : __logf(1.0f + __expf(x)); }
; __device__ __forceinline__ f32x4 mfma16(h8 a, h8 b, f32x4 c) { return __builtin_amdgcn_mfma_f32_16x16x32_f16(a, b, c, 0, 0, 0); }
; __device__ __forceinline__ void phase_rwb(const int wvs, const Params& p, LAS unsigned char* lds, int layer) {
;     ...
;     for (int nt = 0; nt < 24; ++nt) { f32x4 aw = {0.f, 0.f, 0.f, 0.f}, aa = {0.f, 0.f, 0.f, 0.f};
;       const int n4 = nt * 16 + fq * 4; const f32x4 w04 = *(const f32x4*)(w0 + n4), a04 = *(const f32x4*)(a0 + n4);
; #pragma unroll
;       for (int ks = 0; ks < 2; ++ks) { aw = mfma16(*(const LAS h8*)(lds + (nt * 16 + fr) * 144 + ks * 64 + fq * 16), bw[ks], aw); aa = mfma16(*(const LAS h8*)(lds + 55296 + (nt * 16 + fr) * 144 + ks * 64 + fq * 16), ba[ks], aa); }
;       h4 oe, oa;
; #pragma unroll
;       for (int r = 0; r < 4; ++r) { const float wl = -softplusf_(-(w04[r] + aw[r])) - 0.5f; oe[r] = (hf)__expf(wl); oa[r] = (hf)sigmoidf_(a04[r] + aa[r]); }
;       *(h4*)(P + tok * PP + PC_EF + d * 384 + n4) = oe; *(h4*)(P + tok * PP + PC_AF + d * 384 + n4) = oa; }
	v_mfma_f32_16x16x32_f16 v[34:37], v[34:37], v[2:5], 0
	ds_read_b128 v[38:41], v32 offset:57600
	s_waitcnt lgkmcnt(1)
	v_mfma_f32_16x16x32_f16 v[34:37], v[42:45], v[10:13], v[34:37]
	ds_read_b128 v[42:45], v32 offset:57664
	v_add_u32_e32 v32, 0x1200, v32
	s_waitcnt lgkmcnt(1)
	v_mfma_f32_16x16x32_f16 v[38:41], v[38:41], v[6:9], 0
	s_waitcnt vmcnt(1)
	s_nop 2
	v_add_f32_e32 v22, v22, v34
	v_mul_f32_e32 v33, 0xbfb8aa3b, v22
	v_exp_f32_e32 v33, v33
	s_waitcnt lgkmcnt(0)
	v_mfma_f32_16x16x32_f16 v[38:41], v[42:45], v[14:17], v[38:41]
	v_cmp_gt_f32_e32 vcc, s71, v22
	v_add_f32_e32 v33, 1.0, v33
	v_cmp_gt_f32_e64 s[4:5], s34, v33
	s_nop 1
	v_cndmask_b32_e64 v34, 0, 32, s[4:5]
	v_ldexp_f32 v33, v33, v34
	v_log_f32_e32 v33, v33
	s_waitcnt vmcnt(0)
	v_add_f32_e32 v18, v18, v38
	v_mul_f32_e32 v18, 0xbfb8aa3b, v18
	v_exp_f32_e32 v18, v18
	v_mul_f32_e32 v34, 0x3f317217, v33
	v_fma_f32 v34, v33, s66, -v34
	v_fmac_f32_e32 v34, 0x3377d1cf, v33
	v_fmac_f32_e32 v34, 0x3f317217, v33
	v_cmp_lt_f32_e64 s[6:7], |v33|, s65
	v_add_f32_e32 v18, 1.0, v18
	v_add_f32_e32 v19, v19, v39
	v_cndmask_b32_e64 v33, v33, v34, s[6:7]
	v_cndmask_b32_e64 v34, 0, v220, s[4:5]
	v_sub_f32_e32 v33, v33, v34
	v_cndmask_b32_e64 v22, v33, -v22, vcc
	v_rcp_f32_e32 v33, v18
	v_add_f32_e32 v18, v23, v35
	v_mul_f32_e32 v23, 0xbfb8aa3b, v18
	v_exp_f32_e32 v23, v23
	v_mul_f32_e32 v19, 0xbfb8aa3b, v19
	v_exp_f32_e32 v19, v19
	v_cmp_gt_f32_e32 vcc, s71, v18
	v_add_f32_e32 v23, 1.0, v23
	v_cmp_gt_f32_e64 s[4:5], s34, v23
	v_add_f32_e32 v19, 1.0, v19
	v_add_f32_e32 v20, v20, v40
	v_cndmask_b32_e64 v34, 0, 32, s[4:5]
	v_ldexp_f32 v23, v23, v34
	v_log_f32_e32 v23, v23
	v_add_f32_e32 v21, v21, v41
	v_mul_f32_e32 v20, 0xbfb8aa3b, v20
	v_mul_f32_e32 v21, 0xbfb8aa3b, v21
	v_mul_f32_e32 v34, 0x3f317217, v23
	v_fma_f32 v34, v23, s66, -v34
	v_fmac_f32_e32 v34, 0x3377d1cf, v23
	v_fmac_f32_e32 v34, 0x3f317217, v23
	v_cmp_lt_f32_e64 s[6:7], |v23|, s65
	v_exp_f32_e32 v20, v20
	v_exp_f32_e32 v21, v21
	v_cndmask_b32_e64 v23, v23, v34, s[6:7]
	v_cndmask_b32_e64 v34, 0, v220, s[4:5]
	v_sub_f32_e32 v23, v23, v34
	v_cndmask_b32_e64 v18, v23, -v18, vcc
	v_rcp_f32_e32 v23, v19
	v_add_f32_e32 v19, v24, v36
	v_mul_f32_e32 v24, 0xbfb8aa3b, v19
	v_exp_f32_e32 v24, v24
	v_cmp_gt_f32_e32 vcc, s71, v19
	v_sub_f32_e32 v22, -0.5, v22
	v_sub_f32_e32 v18, -0.5, v18
	v_add_f32_e32 v24, 1.0, v24
	v_cmp_gt_f32_e64 s[4:5], s34, v24
	v_mul_f32_e32 v22, 0x3fb8aa3b, v22
	v_mul_f32_e32 v18, 0x3fb8aa3b, v18
	v_cndmask_b32_e64 v34, 0, 32, s[4:5]
	v_ldexp_f32 v24, v24, v34
	v_log_f32_e32 v24, v24
	v_exp_f32_e32 v22, v22
	v_exp_f32_e32 v18, v18
	v_add_f32_e32 v20, 1.0, v20
	v_mul_f32_e32 v34, 0x3f317217, v24
	v_fma_f32 v34, v24, s66, -v34
	v_fmac_f32_e32 v34, 0x3377d1cf, v24
	v_fmac_f32_e32 v34, 0x3f317217, v24
	v_cmp_lt_f32_e64 s[6:7], |v24|, s65
	v_add_f32_e32 v21, 1.0, v21
	v_rcp_f32_e32 v20, v20
	v_cndmask_b32_e64 v24, v24, v34, s[6:7]
	v_cndmask_b32_e64 v34, 0, v220, s[4:5]
	v_sub_f32_e32 v24, v24, v34
	v_cndmask_b32_e64 v19, v24, -v19, vcc
	v_add_f32_e32 v24, v25, v37
	v_mul_f32_e32 v25, 0xbfb8aa3b, v24
	v_exp_f32_e32 v25, v25
	v_cmp_gt_f32_e32 vcc, s71, v24
	v_sub_f32_e32 v19, -0.5, v19
	v_mul_f32_e32 v19, 0x3fb8aa3b, v19
	v_add_f32_e32 v25, 1.0, v25
	v_cmp_gt_f32_e64 s[4:5], s34, v25
	v_exp_f32_e32 v19, v19
	v_rcp_f32_e32 v21, v21
	v_cndmask_b32_e64 v34, 0, 32, s[4:5]
	v_ldexp_f32 v25, v25, v34
	v_log_f32_e32 v25, v25
	v_cvt_pk_f16_f32 v18, v22, v18
	v_cvt_pk_f16_f32 v21, v20, v21
	v_cvt_pk_f16_f32 v20, v33, v23
	v_mul_f32_e32 v34, 0x3f317217, v25
	v_fma_f32 v34, v25, s66, -v34
	v_fmac_f32_e32 v34, 0x3377d1cf, v25
	v_fmac_f32_e32 v34, 0x3f317217, v25
	v_cmp_lt_f32_e64 s[6:7], |v25|, s65
	s_nop 1
	v_cndmask_b32_e64 v25, v25, v34, s[6:7]
	v_cndmask_b32_e64 v34, 0, v220, s[4:5]
	v_sub_f32_e32 v25, v25, v34
	v_cndmask_b32_e64 v24, v25, -v24, vcc
	v_sub_f32_e32 v24, -0.5, v24
	v_mul_f32_e32 v24, 0x3fb8aa3b, v24
	v_exp_f32_e32 v24, v24
	s_nop 0
	v_cvt_pk_f16_f32 v19, v19, v24
	global_store_dwordx2 v[26:27], v[18:19], off offset:-1504
	global_store_dwordx2 v[26:27], v[20:21], off offset:32
	v_lshl_add_u64 v[26:27], v[26:27], 0, 64
	s_cbranch_scc0 .LBB0_1146
	s_mov_b32 s6, 1
	s_mov_b64 s[4:5], 0
	s_and_b64 vcc, exec, s[12:13]
	s_cbranch_vccz .LBB0_1145
